# moba_prep: q/k gain vectors kept resident in free VGPRs (loaded once before the item loop) instead of 4 load-wait round trips per item
# speedup vs baseline: 1.0155x; 1.0017x over previous
; template <int CTRL> __device__ __forceinline__ float dpp_f(float x) { return __int_as_float(__builtin_amdgcn_update_dpp(0, __float_as_int(x), CTRL, 0xF, 0xF, true)); }
; __device__ __forceinline__ void moba_prep_phase(unsigned char* lds, const bf16_t* H, const float* cosT, const float* sinT, const float* qgain, const float* kgain,
;                                                 bf16_t* Qn, bf16_t* Kimg, bf16_t* VT, float* kmean, int bid, int G, int tid) {
;     const int lane = tid & 63, wave = tid >> 6;
;     float* red = (float*)lds;
;     unsigned char* vts = lds + 8192;
;     const int pit0 = (int)(((long)bid * (24 * 64)) / G), pit1 = (int)(((long)(bid + 1) * (24 * 64)) / G);
;     float cs[32], sn[32];
;     int cur_bn = -1;
;     for (int pit = pit0; pit < pit1; ++pit) {
;         const int bn = pit / 12, h = pit - bn * 12, b = bn >> 6, n = bn & 63, bh = b * 12 + h;
;         const int tk = tid >> 1, half = tid & 1, t = n * 256 + tk;
;         const bf16_t* hrow = H + (size_t)(b * SEQ + t) * NMOBA + h * 64 + half * 32;
;         if (bn != cur_bn) {
;             cur_bn = bn;
; #pragma unroll
;             for (int i = 0; i < 8; ++i) { const f32x4 a = *(const f32x4*)(cosT + (size_t)t * 32 + 4 * i), bq = *(const f32x4*)(sinT + (size_t)t * 32 + 4 * i);
;                 cs[4 * i] = a.x; cs[4 * i + 1] = a.y; cs[4 * i + 2] = a.z; cs[4 * i + 3] = a.w; sn[4 * i] = bq.x; sn[4 * i + 1] = bq.y; sn[4 * i + 2] = bq.z; sn[4 * i + 3] = bq.w; }
;         }
;         u32x4 raw[3][4];
; #pragma unroll
;         for (int which = 0; which < 3; ++which)
; #pragma unroll
;             for (int i = 0; i < 4; ++i) raw[which][i] = *(const u32x4*)(hrow + which * 768 + 8 * i);
;         float x[32];
; #pragma unroll
;         for (int which = 0; which < 2; ++which) {
;             const float* gn = which ? kgain : qgain;
; #pragma unroll
;             for (int i = 0; i < 4; ++i) unpack8(raw[which][i], x + 8 * i);
;             float sq = 0.f;
; #pragma unroll
;             for (int i = 0; i < 32; ++i) sq += x[i] * x[i];
;             sq += dpp_f<DPP_XOR1>(sq);
;             const float rs = rsqrtf(sq * (1.0f / 64.0f) + 1e-6f);
; #pragma unroll
;             for (int i = 0; i < 32; ++i) { const float xn = x[i] * rs * gn[half * 32 + i]; const float other = dpp_f<DPP_XOR1>(xn); x[i] = half ? (xn * cs[i] + other * sn[i]) : (xn * cs[i] - other * sn[i]); }
.LBB0_500:
	s_mov_b32 s29, s47
	s_cmp_ge_i32 s22, s28
	s_cbranch_scc1 .LBB0_572
	v_ashrrev_i32_e32 v154, 1, v0
	s_waitcnt lgkmcnt(0)
	v_and_b32_e32 v1, 14, v0
	v_lshrrev_b32_e32 v10, 2, v154
	v_cmp_eq_u32_e64 s[36:37], 0, v1
	v_and_b32_e32 v1, 24, v0
	v_and_b32_e32 v10, 4, v10
	v_and_b32_e32 v11, 0x7fffffe3, v154
	s_lshl_b32 s30, s61, 6
	v_readlane_b32 s44, v252, 8
	v_lshlrev_b32_e32 v4, 6, v154
	v_lshlrev_b32_e32 v7, 4, v0
	v_or3_b32 v1, v11, v1, v10
	v_readlane_b32 s26, v252, 28
	s_lshl_b64 s[0:1], s[30:31], 2
	v_readlane_b32 s48, v252, 12
	s_waitcnt lgkmcnt(1)
	v_and_b32_e32 v3, 1, v0
	v_ashrrev_i32_e32 v5, 31, v4
	v_lshlrev_b32_e32 v10, 1, v1
	v_ashrrev_i32_e32 v1, 31, v0
	v_readlane_b32 s27, v252, 29
	v_and_b32_e32 v138, 0x1f0, v7
	v_readlane_b32 s49, v252, 13
	s_add_u32 s24, s48, s0
	v_lshl_add_u64 v[4:5], v[4:5], 1, s[82:83]
	v_lshl_add_u64 v[112:113], v[0:1], 2, s[26:27]
	v_add_u32_e32 v1, 0, v138
	v_lshl_add_u64 v[114:115], s[84:85], 0, v[138:139]
	v_lshlrev_b32_e32 v138, 6, v3
	v_readlane_b32 s46, v252, 10
	s_addc_u32 s25, s49, s1
	v_lshl_add_u64 v[120:121], v[4:5], 0, v[138:139]
	v_add_u32_e32 v4, 0x200, v0
	v_readlane_b32 s47, v252, 11
	s_add_u32 s0, s46, s0
	s_movk_i32 s23, 0x210
	v_ashrrev_i32_e32 v4, 5, v4
	s_addc_u32 s1, s47, s1
	v_lshlrev_b32_e32 v6, 7, v3
	v_and_b32_e32 v9, 0xffffff00, v7
	v_cmp_gt_i32_e64 s[38:39], 64, v0
	v_lshl_add_u32 v155, v0, 2, 0
	v_ashrrev_i32_e32 v11, 5, v0
	v_mov_b32_e32 v7, v139
	v_mul_lo_u32 v5, v4, s23
	v_lshlrev_b32_e32 v124, 8, v4
	v_add_u32_e32 v4, 0x400, v0
	v_add_u32_e32 v0, 0x600, v0
	v_readlane_b32 s45, v252, 9
	v_lshl_add_u64 v[116:117], s[0:1], 0, v[6:7]
	s_movk_i32 s0, 0x4200
	v_ashrrev_i32_e32 v4, 5, v4
	v_ashrrev_i32_e32 v0, 5, v0
	s_waitcnt lgkmcnt(0)
	v_lshlrev_b32_e32 v2, 5, v3
	v_cmp_eq_u32_e32 vcc, 0, v3
	v_add_u32_e32 v8, 0, v6
	v_mul_lo_u32 v12, v11, s23
	v_lshl_add_u64 v[118:119], s[24:25], 0, v[6:7]
	v_mad_u32_u24 v3, v3, s0, 0
	v_lshlrev_b32_e32 v122, 8, v11
	v_mul_lo_u32 v6, v4, s23
	v_lshlrev_b32_e32 v126, 8, v4
	v_mul_lo_u32 v4, v0, s23
	v_lshlrev_b32_e32 v128, 8, v0
	v_readlane_b32 s42, v252, 24
	v_readlane_b32 s44, v252, 26
	v_ashrrev_i32_e32 v123, 31, v122
	v_ashrrev_i32_e32 v125, 31, v124
	v_ashrrev_i32_e32 v127, 31, v126
	v_ashrrev_i32_e32 v129, 31, v128
	s_lshl_b32 s23, s22, 6
	s_mov_b32 s24, -1
	v_lshlrev_b32_e32 v138, 1, v2
	v_add_u32_e32 v156, v3, v10
	v_add_u32_e32 v157, v1, v12
	v_add_u32_e32 v158, v1, v5
	v_add_u32_e32 v159, v1, v6
	v_add_u32_e32 v160, v1, v4
	v_add_u32_e32 v161, v8, v9
	v_readlane_b32 s43, v252, 25
	v_readlane_b32 s45, v252, 27
	v_readlane_b32 s50, v252, 14
	v_readlane_b32 s51, v252, 15
	v_readlane_b32 s52, v252, 16
	v_readlane_b32 s53, v252, 17
	v_readlane_b32 s54, v252, 18
	v_readlane_b32 s55, v252, 19
	v_readlane_b32 s56, v252, 20
	v_readlane_b32 s57, v252, 21
	v_readlane_b32 s58, v252, 22
	v_readlane_b32 s59, v252, 23
	global_load_dwordx4 v[186:189], v[116:117], off offset:16
	global_load_dwordx4 v[190:193], v[116:117], off offset:32
	global_load_dwordx4 v[194:197], v[116:117], off offset:48
	global_load_dwordx4 v[198:201], v[116:117], off offset:64
	global_load_dwordx4 v[208:211], v[116:117], off offset:80
	global_load_dwordx4 v[212:215], v[116:117], off offset:96
	global_load_dwordx4 v[216:219], v[116:117], off offset:112
	global_load_dwordx4 v[220:223], v[118:119], off
	global_load_dwordx4 v[228:231], v[118:119], off offset:16
	global_load_dwordx4 v[232:235], v[118:119], off offset:32
	global_load_dwordx4 v[236:239], v[118:119], off offset:48
	global_load_dwordx4 v[240:243], v[118:119], off offset:64
	global_load_dwordx4 v[244:247], v[118:119], off offset:80
	global_load_dwordx4 v[64:67], v[118:119], off offset:96
	global_load_dwordx4 v[68:71], v[118:119], off offset:112
	s_waitcnt vmcnt(0)
	v_mov_b32_e32 v185, v64
	v_mov_b32_e32 v202, v65
	v_mov_b32_e32 v203, v66
	v_mov_b32_e32 v224, v67
	v_mov_b32_e32 v225, v68
	v_mov_b32_e32 v226, v69
	v_mov_b32_e32 v248, v70
	v_mov_b32_e32 v249, v71
	s_branch .LBB0_503

; template <int CTRL> __device__ __forceinline__ float dpp_f(float x) { return __int_as_float(__builtin_amdgcn_update_dpp(0, __float_as_int(x), CTRL, 0xF, 0xF, true)); }
; __device__ __forceinline__ void moba_prep_phase(unsigned char* lds, const bf16_t* H, const float* cosT, const float* sinT, const float* qgain, const float* kgain,
;                                                 bf16_t* Qn, bf16_t* Kimg, bf16_t* VT, float* kmean, int bid, int G, int tid) {
;     ...
;         u32x4 raw[3][4];
; #pragma unroll
;         for (int which = 0; which < 3; ++which)
; #pragma unroll
;             for (int i = 0; i < 4; ++i) raw[which][i] = *(const u32x4*)(hrow + which * 768 + 8 * i);
;         float x[32];
; #pragma unroll
;         for (int which = 0; which < 2; ++which) {
;             const float* gn = which ? kgain : qgain;
; #pragma unroll
;             for (int i = 0; i < 4; ++i) unpack8(raw[which][i], x + 8 * i);
;             float sq = 0.f;
; #pragma unroll
;             for (int i = 0; i < 32; ++i) sq += x[i] * x[i];
;             sq += dpp_f<DPP_XOR1>(sq);
;             const float rs = rsqrtf(sq * (1.0f / 64.0f) + 1e-6f);
; #pragma unroll
;             for (int i = 0; i < 32; ++i) { const float xn = x[i] * rs * gn[half * 32 + i]; const float other = dpp_f<DPP_XOR1>(xn); x[i] = half ? (xn * cs[i] + other * sn[i]) : (xn * cs[i] - other * sn[i]); }
.LBB0_505:
	s_ashr_i32 s25, s1, 6
	s_waitcnt vmcnt(16)
	v_lshl_add_u32 v66, s25, 14, v64
	v_mov_b64_e32 v[64:65], s[78:79]
	s_mul_i32 s27, s1, 12
	v_mad_i64_i32 v[64:65], s[40:41], v66, s60, v[64:65]
	s_mulk_i32 s1, 0xfd00
	s_add_i32 s40, s23, s1
	s_ashr_i32 s41, s40, 31
	v_lshl_add_u64 v[64:65], s[40:41], 1, v[64:65]
	v_lshl_add_u64 v[64:65], v[64:65], 0, v[138:139]
	global_load_dwordx4 v[168:171], v[64:65], off offset:48
	global_load_dwordx4 v[132:135], v[64:65], off offset:32
	global_load_dwordx4 v[148:151], v[64:65], off offset:16
	global_load_dwordx4 v[98:101], v[64:65], off
	global_load_dwordx4 v[80:83], v[64:65], off offset:1584
	global_load_dwordx4 v[84:87], v[64:65], off offset:1568
	global_load_dwordx4 v[88:91], v[64:65], off offset:1552
	global_load_dwordx4 v[92:95], v[64:65], off offset:1536
	global_load_dwordx4 v[76:79], v[64:65], off offset:3072
	global_load_dwordx4 v[72:75], v[64:65], off offset:3088
	global_load_dwordx4 v[68:71], v[64:65], off offset:3104
	s_nop 0
	global_load_dwordx4 v[64:67], v[64:65], off offset:3120
	s_mul_i32 s26, s25, 12
	s_sub_i32 s26, s26, s27
	s_add_i32 s26, s22, s26
	s_lshl_b32 s1, s26, 6
	s_or_b32 s46, s1, s0
	s_ashr_i32 s47, s46, 31
	s_ashr_i32 s27, s26, 31
	s_lshl_b64 s[40:41], s[46:47], 15
	s_lshl_b64 s[0:1], s[26:27], 21
	s_add_u32 s0, s62, s0
	s_addc_u32 s1, s63, s1
	v_lshl_add_u64 v[130:131], s[0:1], 0, v[96:97]
	s_waitcnt vmcnt(10)
	v_lshlrev_b32_e32 v164, 16, v134
	v_and_b32_e32 v163, 0xffff0000, v134
	s_waitcnt vmcnt(8)
	v_and_b32_e32 v111, 0xffff0000, v98
	v_lshlrev_b32_e32 v172, 16, v98
	v_mul_f32_e32 v134, v111, v111
	v_lshlrev_b32_e32 v110, 16, v99
	v_fmac_f32_e32 v134, v172, v172
	v_and_b32_e32 v109, 0xffff0000, v99
	v_fmac_f32_e32 v134, v110, v110
	v_lshlrev_b32_e32 v108, 16, v100
	v_fmac_f32_e32 v134, v109, v109
	v_and_b32_e32 v107, 0xffff0000, v100
	v_fmac_f32_e32 v134, v108, v108
	v_lshlrev_b32_e32 v106, 16, v101
	v_fmac_f32_e32 v134, v107, v107
	v_and_b32_e32 v105, 0xffff0000, v101
	v_fmac_f32_e32 v134, v106, v106
	v_lshlrev_b32_e32 v104, 16, v148
	v_fmac_f32_e32 v134, v105, v105
	v_and_b32_e32 v103, 0xffff0000, v148
	v_fmac_f32_e32 v134, v104, v104
	v_lshlrev_b32_e32 v102, 16, v149
	v_fmac_f32_e32 v134, v103, v103
	v_and_b32_e32 v101, 0xffff0000, v149
	v_fmac_f32_e32 v134, v102, v102
	v_lshlrev_b32_e32 v100, 16, v150
	v_fmac_f32_e32 v134, v101, v101
	v_and_b32_e32 v99, 0xffff0000, v150
	v_fmac_f32_e32 v134, v100, v100
	v_lshlrev_b32_e32 v98, 16, v151
	v_fmac_f32_e32 v134, v99, v99
	v_and_b32_e32 v97, 0xffff0000, v151
	v_fmac_f32_e32 v134, v98, v98
	v_lshlrev_b32_e32 v96, 16, v132
	v_fmac_f32_e32 v134, v97, v97
	v_and_b32_e32 v167, 0xffff0000, v132
	v_fmac_f32_e32 v134, v96, v96
	v_lshlrev_b32_e32 v166, 16, v133
	v_fmac_f32_e32 v134, v167, v167
	v_and_b32_e32 v165, 0xffff0000, v133
	v_fmac_f32_e32 v134, v166, v166
	v_fmac_f32_e32 v134, v165, v165
	v_fmac_f32_e32 v134, v164, v164
	v_and_b32_e32 v152, 0xffff0000, v135
	v_lshlrev_b32_e32 v153, 16, v135
	v_fmac_f32_e32 v134, v163, v163
	v_pk_mul_f32 v[132:133], v[152:153], v[152:153]
	v_and_b32_e32 v150, 0xffff0000, v168
	v_add_f32_e32 v133, v133, v134
	v_lshlrev_b32_e32 v151, 16, v168
	v_add_f32_e32 v134, v132, v133
	v_pk_mul_f32 v[132:133], v[150:151], v[150:151]
	v_and_b32_e32 v148, 0xffff0000, v169
	v_add_f32_e32 v133, v133, v134
	v_lshlrev_b32_e32 v149, 16, v169
	v_add_f32_e32 v134, v132, v133
	v_pk_mul_f32 v[132:133], v[148:149], v[148:149]
	v_lshlrev_b32_e32 v135, 16, v170
	v_add_f32_e32 v133, v133, v134
	v_and_b32_e32 v134, 0xffff0000, v170
	v_add_f32_e32 v162, v132, v133
	v_pk_mul_f32 v[132:133], v[134:135], v[134:135]
	s_nop 0
	v_add_f32_e32 v133, v133, v162
	v_add_f32_e32 v162, v132, v133
	v_and_b32_e32 v132, 0xffff0000, v171
	v_lshlrev_b32_e32 v133, 16, v171
	v_pk_mul_f32 v[168:169], v[132:133], v[132:133]
	s_nop 0
	v_add_f32_e32 v162, v169, v162
	v_add_f32_e32 v162, v168, v162
	s_nop 1
	v_add_f32_dpp v162, v162, v162 quad_perm:[1,0,3,2] row_mask:0xf bank_mask:0xf bound_ctrl:1
	v_fmamk_f32 v162, v162, 0x3c800000, v137
	v_cmp_gt_f32_e64 s[0:1], s4, v162
	v_mul_f32_e32 v168, 0x4b800000, v162
	s_nop 0
	v_cndmask_b32_e64 v162, v162, v168, s[0:1]
	v_rsq_f32_e32 v162, v162
	s_nop 0
	v_mul_f32_e32 v168, 0x45800000, v162
	v_cndmask_b32_e64 v162, v162, v168, s[0:1]
	v_mul_f32_e32 v184, v162, v172
	v_mov_b32_e32 v180, v194
	v_mov_b32_e32 v181, v195
	v_mov_b32_e32 v182, v196
	v_mov_b32_e32 v183, v197
	v_mov_b32_e32 v176, v190
	v_mov_b32_e32 v177, v191
	v_mov_b32_e32 v178, v192
	v_mov_b32_e32 v179, v193
	v_mov_b32_e32 v172, v186
	v_mov_b32_e32 v173, v187
	v_mov_b32_e32 v174, v188
	v_mov_b32_e32 v175, v189
	global_load_dwordx4 v[168:171], v[116:117], off
	v_mul_f32_e32 v111, v162, v111
	v_mul_f32_e32 v110, v162, v110
	v_mul_f32_e32 v109, v162, v109
	v_mul_f32_e32 v108, v162, v108
	v_mul_f32_e32 v107, v162, v107
	v_mul_f32_e32 v106, v162, v106
	v_mul_f32_e32 v105, v162, v105
	v_mul_f32_e32 v104, v162, v104
	v_mul_f32_e32 v103, v162, v103
	v_mul_f32_e32 v102, v162, v102
	v_mul_f32_e32 v101, v162, v101
	v_mul_f32_e32 v100, v162, v100
	v_mul_f32_e32 v99, v162, v99
	v_mul_f32_e32 v98, v162, v98
	v_mul_f32_e32 v97, v162, v97
	s_waitcnt vmcnt(1)
	v_mul_f32_e32 v100, v180, v100
	s_waitcnt vmcnt(1)
	v_mul_f32_e32 v104, v176, v104
	s_waitcnt vmcnt(1)
	v_mul_f32_e32 v108, v172, v108
	s_waitcnt vmcnt(0)
; template <int CTRL> __device__ __forceinline__ float dpp_f(float x) { return __int_as_float(__builtin_amdgcn_update_dpp(0, __float_as_int(x), CTRL, 0xF, 0xF, true)); }
; __device__ __forceinline__ void moba_prep_phase(unsigned char* lds, const bf16_t* H, const float* cosT, const float* sinT, const float* qgain, const float* kgain,
;                                                 bf16_t* Qn, bf16_t* Kimg, bf16_t* VT, float* kmean, int bid, int G, int tid) {
;     ...
;             const float rs = rsqrtf(sq * (1.0f / 64.0f) + 1e-6f);
; #pragma unroll
;             for (int i = 0; i < 32; ++i) { const float xn = x[i] * rs * gn[half * 32 + i]; const float other = dpp_f<DPP_XOR1>(xn); x[i] = half ? (xn * cs[i] + other * sn[i]) : (xn * cs[i] - other * sn[i]); }
;             bf16_t* dst = which ? (Kimg + (size_t)(bh * 64 + n) * 16384 + tk * 64 + half * 32) : (Qn + ((size_t)bh * SEQ + t) * 64 + half * 32);
;             if (!which) {
; #pragma unroll
;                 for (int i = 0; i < 32; ++i) x[i] *= QSCALE;
	v_mul_f32_e32 v111, v169, v111
	v_mul_f32_e32 v110, v170, v110
	v_mul_f32_e32 v109, v171, v109
	v_mul_f32_dpp v169, v111, v21 quad_perm:[1,0,3,2] row_mask:0xf bank_mask:0xf bound_ctrl:1
	v_cndmask_b32_e64 v169, v169, -v169, vcc
	v_fmac_f32_e32 v169, v1, v111
	v_mul_f32_dpp v111, v110, v22 quad_perm:[1,0,3,2] row_mask:0xf bank_mask:0xf bound_ctrl:1
	v_cndmask_b32_e64 v170, v111, -v111, vcc
	v_fmac_f32_e32 v170, v2, v110
	v_mul_f32_dpp v110, v109, v23 quad_perm:[1,0,3,2] row_mask:0xf bank_mask:0xf bound_ctrl:1
	v_cndmask_b32_e64 v171, v110, -v110, vcc
	v_fmac_f32_e32 v171, v3, v109
	v_mul_f32_dpp v109, v108, v24 quad_perm:[1,0,3,2] row_mask:0xf bank_mask:0xf bound_ctrl:1
	v_cndmask_b32_e64 v172, v109, -v109, vcc
	v_mul_f32_e32 v107, v173, v107
	v_fmac_f32_e32 v172, v4, v108
	v_mul_f32_e32 v106, v174, v106
	v_mul_f32_dpp v108, v107, v25 quad_perm:[1,0,3,2] row_mask:0xf bank_mask:0xf bound_ctrl:1
	v_cndmask_b32_e64 v173, v108, -v108, vcc
	v_fmac_f32_e32 v173, v5, v107
	v_mul_f32_dpp v107, v106, v26 quad_perm:[1,0,3,2] row_mask:0xf bank_mask:0xf bound_ctrl:1
	v_cndmask_b32_e64 v174, v107, -v107, vcc
	v_mul_f32_e32 v105, v175, v105
	v_fmac_f32_e32 v174, v6, v106
	v_mul_f32_e32 v103, v177, v103
	v_mul_f32_dpp v106, v105, v27 quad_perm:[1,0,3,2] row_mask:0xf bank_mask:0xf bound_ctrl:1
	v_cndmask_b32_e64 v175, v106, -v106, vcc
	v_fmac_f32_e32 v175, v7, v105
	v_mul_f32_dpp v105, v104, v28 quad_perm:[1,0,3,2] row_mask:0xf bank_mask:0xf bound_ctrl:1
	v_cndmask_b32_e64 v176, v105, -v105, vcc
	v_fmac_f32_e32 v176, v8, v104
	v_mul_f32_dpp v104, v103, v29 quad_perm:[1,0,3,2] row_mask:0xf bank_mask:0xf bound_ctrl:1
	v_cndmask_b32_e64 v177, v104, -v104, vcc
	v_mul_f32_e32 v102, v178, v102
	v_fmac_f32_e32 v177, v9, v103
	v_mul_f32_e32 v101, v179, v101
	v_mul_f32_dpp v103, v102, v30 quad_perm:[1,0,3,2] row_mask:0xf bank_mask:0xf bound_ctrl:1
	v_cndmask_b32_e64 v178, v103, -v103, vcc
	v_fmac_f32_e32 v178, v10, v102
	v_mul_f32_dpp v102, v101, v31 quad_perm:[1,0,3,2] row_mask:0xf bank_mask:0xf bound_ctrl:1
	v_cndmask_b32_e64 v179, v102, -v102, vcc
	v_fmac_f32_e32 v179, v11, v101
	v_mul_f32_dpp v101, v100, v32 quad_perm:[1,0,3,2] row_mask:0xf bank_mask:0xf bound_ctrl:1
	v_cndmask_b32_e64 v180, v101, -v101, vcc
	v_mul_f32_e32 v99, v181, v99
	v_fmac_f32_e32 v180, v12, v100
	v_mul_f32_e32 v98, v182, v98
	v_mul_f32_dpp v100, v99, v33 quad_perm:[1,0,3,2] row_mask:0xf bank_mask:0xf bound_ctrl:1
	v_cndmask_b32_e64 v181, v100, -v100, vcc
	v_fmac_f32_e32 v181, v13, v99
	v_mul_f32_dpp v99, v98, v34 quad_perm:[1,0,3,2] row_mask:0xf bank_mask:0xf bound_ctrl:1
	v_mul_f32_e32 v184, v168, v184
	v_cndmask_b32_e64 v182, v99, -v99, vcc
	v_mul_f32_e32 v97, v183, v97
	v_mul_f32_dpp v168, v184, v20 quad_perm:[1,0,3,2] row_mask:0xf bank_mask:0xf bound_ctrl:1
	v_fmac_f32_e32 v182, v14, v98
	v_mul_f32_dpp v98, v97, v35 quad_perm:[1,0,3,2] row_mask:0xf bank_mask:0xf bound_ctrl:1
	v_cndmask_b32_e64 v168, v168, -v168, vcc
	v_cndmask_b32_e64 v183, v98, -v98, vcc
	v_fmac_f32_e32 v168, v0, v184
	v_fmac_f32_e32 v183, v15, v97
	v_mul_f32_e32 v184, v162, v96
	v_mov_b32_e32 v96, v216
	v_mov_b32_e32 v97, v217
	v_mov_b32_e32 v98, v218
	v_mov_b32_e32 v99, v219
	v_mov_b32_e32 v100, v212
	v_mov_b32_e32 v101, v213
	v_mov_b32_e32 v102, v214
	v_mov_b32_e32 v103, v215
	v_mov_b32_e32 v104, v208
	v_mov_b32_e32 v105, v209
	v_mov_b32_e32 v106, v210
	v_mov_b32_e32 v107, v211
	v_mov_b32_e32 v108, v198
	v_mov_b32_e32 v109, v199
	v_mov_b32_e32 v110, v200
	v_mov_b32_e32 v111, v201
	s_waitcnt vmcnt(0)
	v_mul_f32_e32 v108, v184, v108
	s_nop 1
	v_mul_f32_dpp v184, v108, v36 quad_perm:[1,0,3,2] row_mask:0xf bank_mask:0xf bound_ctrl:1
	v_cndmask_b32_e64 v184, v184, -v184, vcc
	v_fmac_f32_e32 v184, v16, v108
	v_mul_f32_e32 v108, v162, v167
	v_mul_f32_e32 v108, v108, v109
	v_mul_f32_e32 v167, 0x3e38aa3b, v168
	s_nop 0
	v_mul_f32_dpp v109, v108, v37 quad_perm:[1,0,3,2] row_mask:0xf bank_mask:0xf bound_ctrl:1
	v_cndmask_b32_e64 v109, v109, -v109, vcc
	v_fmac_f32_e32 v109, v17, v108
	v_mul_f32_e32 v108, v162, v166
	v_mul_f32_e32 v108, v108, v110
	v_mul_f32_e32 v166, 0x3e38aa3b, v170
	v_mul_f32_e32 v109, 0x3e38aa3b, v109
	v_mul_f32_dpp v110, v108, v38 quad_perm:[1,0,3,2] row_mask:0xf bank_mask:0xf bound_ctrl:1
	v_cndmask_b32_e64 v110, v110, -v110, vcc
	v_fmac_f32_e32 v110, v18, v108
	v_mul_f32_e32 v108, v162, v165
	v_mul_f32_e32 v108, v108, v111
	v_mul_f32_e32 v165, 0x3e38aa3b, v172
	v_mul_f32_e32 v110, 0x3e38aa3b, v110
	v_mul_f32_dpp v111, v108, v39 quad_perm:[1,0,3,2] row_mask:0xf bank_mask:0xf bound_ctrl:1
	v_cndmask_b32_e64 v111, v111, -v111, vcc
	v_fmac_f32_e32 v111, v19, v108
	v_mul_f32_e32 v108, v162, v164
	v_mul_f32_e32 v104, v108, v104
	v_mul_f32_e32 v164, 0x3e38aa3b, v174
	v_mul_f32_e32 v111, 0x3e38aa3b, v111
	v_mul_f32_dpp v108, v104, v40 quad_perm:[1,0,3,2] row_mask:0xf bank_mask:0xf bound_ctrl:1
	v_cndmask_b32_e64 v108, v108, -v108, vcc
	v_fmac_f32_e32 v108, v52, v104
	v_mul_f32_e32 v104, v162, v163
	v_mul_f32_e32 v104, v104, v105
	v_mul_f32_e32 v108, 0x3e38aa3b, v108
	v_mul_f32_e32 v163, 0x3e38aa3b, v176
	v_mul_f32_dpp v105, v104, v41 quad_perm:[1,0,3,2] row_mask:0xf bank_mask:0xf bound_ctrl:1
	v_cndmask_b32_e64 v105, v105, -v105, vcc
	v_fmac_f32_e32 v105, v53, v104
	v_mul_f32_e32 v104, v162, v153
	v_mul_f32_e32 v104, v104, v106
	v_mul_f32_e32 v153, 0x3e38aa3b, v178
	v_mul_f32_e32 v105, 0x3e38aa3b, v105
	v_mul_f32_dpp v106, v104, v42 quad_perm:[1,0,3,2] row_mask:0xf bank_mask:0xf bound_ctrl:1
	v_cndmask_b32_e64 v106, v106, -v106, vcc
	v_fmac_f32_e32 v106, v54, v104
	v_mul_f32_e32 v104, v162, v152
	v_mul_f32_e32 v104, v104, v107
	v_mul_f32_e32 v152, 0x3e38aa3b, v179
	v_mul_f32_e32 v106, 0x3e38aa3b, v106
; __device__ __forceinline__ u32x4 pack8(const float* f) { u32x4 w; w.x = cvt_pk_bf16(f[0], f[1]); w.y = cvt_pk_bf16(f[2], f[3]); w.z = cvt_pk_bf16(f[4], f[5]); w.w = cvt_pk_bf16(f[6], f[7]); return w; }
; template <int CTRL> __device__ __forceinline__ float dpp_f(float x) { return __int_as_float(__builtin_amdgcn_update_dpp(0, __float_as_int(x), CTRL, 0xF, 0xF, true)); }
; __device__ __forceinline__ void moba_prep_phase(unsigned char* lds, const bf16_t* H, const float* cosT, const float* sinT, const float* qgain, const float* kgain,
;                                                 bf16_t* Qn, bf16_t* Kimg, bf16_t* VT, float* kmean, int bid, int G, int tid) {
;     ...
;             for (int i = 0; i < 4; ++i) unpack8(raw[which][i], x + 8 * i);
;             float sq = 0.f;
; #pragma unroll
;             for (int i = 0; i < 32; ++i) sq += x[i] * x[i];
;             sq += dpp_f<DPP_XOR1>(sq);
;             const float rs = rsqrtf(sq * (1.0f / 64.0f) + 1e-6f);
; #pragma unroll
;             for (int i = 0; i < 32; ++i) { const float xn = x[i] * rs * gn[half * 32 + i]; const float other = dpp_f<DPP_XOR1>(xn); x[i] = half ? (xn * cs[i] + other * sn[i]) : (xn * cs[i] - other * sn[i]); }
;             bf16_t* dst = which ? (Kimg + (size_t)(bh * 64 + n) * 16384 + tk * 64 + half * 32) : (Qn + ((size_t)bh * SEQ + t) * 64 + half * 32);
;             if (!which) {
; #pragma unroll
;                 for (int i = 0; i < 32; ++i) x[i] *= QSCALE;
;             }
; #pragma unroll
;             for (int i = 0; i < 4; ++i) *(u32x4*)(dst + 8 * i) = pack8(x + 8 * i);
	v_mul_f32_dpp v107, v104, v43 quad_perm:[1,0,3,2] row_mask:0xf bank_mask:0xf bound_ctrl:1
	v_cndmask_b32_e64 v107, v107, -v107, vcc
	v_fmac_f32_e32 v107, v55, v104
	v_mul_f32_e32 v104, v162, v151
	v_mul_f32_e32 v100, v104, v100
	v_mul_f32_e32 v107, 0x3e38aa3b, v107
	v_mul_f32_e32 v151, 0x3e38aa3b, v180
	v_mul_f32_dpp v104, v100, v44 quad_perm:[1,0,3,2] row_mask:0xf bank_mask:0xf bound_ctrl:1
	v_cndmask_b32_e64 v104, v104, -v104, vcc
	v_fmac_f32_e32 v104, v56, v100
	v_mul_f32_e32 v100, v162, v150
	v_mul_f32_e32 v100, v100, v101
	v_mul_f32_e32 v104, 0x3e38aa3b, v104
	s_nop 0
	v_mul_f32_dpp v101, v100, v45 quad_perm:[1,0,3,2] row_mask:0xf bank_mask:0xf bound_ctrl:1
	v_cndmask_b32_e64 v150, v101, -v101, vcc
	v_fmac_f32_e32 v150, v57, v100
	v_mul_f32_e32 v100, v162, v149
	v_mul_f32_e32 v100, v100, v102
	v_mul_f32_e32 v149, 0x3e38aa3b, v182
	s_nop 0
	v_mul_f32_dpp v101, v100, v46 quad_perm:[1,0,3,2] row_mask:0xf bank_mask:0xf bound_ctrl:1
	v_cndmask_b32_e64 v102, v101, -v101, vcc
	v_fmac_f32_e32 v102, v58, v100
	v_mul_f32_e32 v100, v162, v148
	v_mul_f32_e32 v100, v100, v103
	v_mul_f32_e32 v148, 0x3e38aa3b, v183
	v_mul_f32_e32 v102, 0x3e38aa3b, v102
	v_mul_f32_dpp v101, v100, v47 quad_perm:[1,0,3,2] row_mask:0xf bank_mask:0xf bound_ctrl:1
	v_cndmask_b32_e64 v103, v101, -v101, vcc
	v_fmac_f32_e32 v103, v59, v100
	v_mul_f32_e32 v100, v162, v135
	v_mul_f32_e32 v96, v100, v96
	v_mul_f32_e32 v103, 0x3e38aa3b, v103
	s_nop 0
	v_mul_f32_dpp v100, v96, v48 quad_perm:[1,0,3,2] row_mask:0xf bank_mask:0xf bound_ctrl:1
	v_cndmask_b32_e64 v135, v100, -v100, vcc
	v_fmac_f32_e32 v135, v60, v96
	v_mul_f32_e32 v96, v162, v134
	v_mul_f32_e32 v96, v96, v97
	v_lshl_add_u64 v[100:101], v[130:131], 0, v[138:139]
	v_mul_f32_e32 v134, 0x3e38aa3b, v150
	v_mul_f32_dpp v97, v96, v49 quad_perm:[1,0,3,2] row_mask:0xf bank_mask:0xf bound_ctrl:1
	v_cndmask_b32_e64 v97, v97, -v97, vcc
	v_fmac_f32_e32 v97, v61, v96
	v_mul_f32_e32 v96, v162, v133
	v_mul_f32_e32 v96, v96, v98
	v_mul_f32_e32 v150, 0x3e38aa3b, v181
	v_mul_f32_e32 v133, 0x3e38aa3b, v135
	v_mul_f32_dpp v98, v96, v50 quad_perm:[1,0,3,2] row_mask:0xf bank_mask:0xf bound_ctrl:1
	v_cndmask_b32_e64 v98, v98, -v98, vcc
	v_fmac_f32_e32 v98, v62, v96
	v_mul_f32_e32 v96, v162, v132
	v_mul_f32_e32 v96, v96, v99
	v_mul_f32_e32 v131, 0x3e38aa3b, v98
	v_mul_f32_e32 v132, 0x3e38aa3b, v97
	v_mul_f32_dpp v99, v96, v51 quad_perm:[1,0,3,2] row_mask:0xf bank_mask:0xf bound_ctrl:1
	v_cndmask_b32_e64 v99, v99, -v99, vcc
	v_fmac_f32_e32 v99, v63, v96
	v_mul_f32_e32 v130, 0x3e38aa3b, v99
	v_mul_f32_e32 v99, 0x3e38aa3b, v175
	v_mul_f32_e32 v98, 0x3e38aa3b, v173
	v_mul_f32_e32 v97, 0x3e38aa3b, v171
	v_mul_f32_e32 v96, 0x3e38aa3b, v169
	v_cvt_pk_bf16_f32 v96, v167, v96
	v_cvt_pk_bf16_f32 v97, v166, v97
	v_cvt_pk_bf16_f32 v98, v165, v98
	v_cvt_pk_bf16_f32 v99, v164, v99
	v_mul_f32_e32 v162, 0x3e38aa3b, v177
	global_store_dwordx4 v[100:101], v[96:99], off
	v_and_b32_e32 v164, 0xffff0000, v92
	v_mul_f32_e32 v135, 0x3e38aa3b, v184
	v_cvt_pk_bf16_f32 v96, v163, v162
	v_cvt_pk_bf16_f32 v97, v153, v152
	v_cvt_pk_bf16_f32 v98, v151, v150
	v_cvt_pk_bf16_f32 v99, v149, v148
	global_store_dwordx4 v[100:101], v[96:99], off offset:16
	v_lshlrev_b32_e32 v165, 16, v92
	v_lshlrev_b32_e32 v163, 16, v93
	v_cvt_pk_bf16_f32 v96, v135, v109
	v_cvt_pk_bf16_f32 v97, v110, v111
	v_cvt_pk_bf16_f32 v98, v108, v105
	v_cvt_pk_bf16_f32 v99, v106, v107
	v_lshlrev_b32_e32 v108, 16, v86
	v_and_b32_e32 v107, 0xffff0000, v86
	v_mul_f32_e32 v86, v164, v164
	v_fmac_f32_e32 v86, v165, v165
	v_and_b32_e32 v162, 0xffff0000, v93
	v_fmac_f32_e32 v86, v163, v163
	v_lshlrev_b32_e32 v153, 16, v94
	v_fmac_f32_e32 v86, v162, v162
	v_and_b32_e32 v152, 0xffff0000, v94
	v_fmac_f32_e32 v86, v153, v153
	v_lshlrev_b32_e32 v151, 16, v95
	v_fmac_f32_e32 v86, v152, v152
	v_and_b32_e32 v150, 0xffff0000, v95
	v_fmac_f32_e32 v86, v151, v151
	v_lshlrev_b32_e32 v149, 16, v88
	v_fmac_f32_e32 v86, v150, v150
	v_and_b32_e32 v148, 0xffff0000, v88
	v_fmac_f32_e32 v86, v149, v149
	v_lshlrev_b32_e32 v135, 16, v89
	v_fmac_f32_e32 v86, v148, v148
	global_store_dwordx4 v[100:101], v[96:99], off offset:32
	v_fmac_f32_e32 v86, v135, v135
	v_lshlrev_b32_e32 v166, 16, v84
	v_cvt_pk_bf16_f32 v96, v104, v134
	v_and_b32_e32 v134, 0xffff0000, v89
	v_cvt_pk_bf16_f32 v97, v102, v103
	v_cvt_pk_bf16_f32 v98, v133, v132
	v_lshlrev_b32_e32 v133, 16, v90
	v_fmac_f32_e32 v86, v134, v134
	v_and_b32_e32 v132, 0xffff0000, v90
	v_fmac_f32_e32 v86, v133, v133
	v_cvt_pk_bf16_f32 v99, v131, v130
	v_lshlrev_b32_e32 v131, 16, v91
	v_fmac_f32_e32 v86, v132, v132
	v_and_b32_e32 v130, 0xffff0000, v91
	v_fmac_f32_e32 v86, v131, v131
	v_fmac_f32_e32 v86, v130, v130
	v_and_b32_e32 v111, 0xffff0000, v84
	v_fmac_f32_e32 v86, v166, v166
	v_lshlrev_b32_e32 v110, 16, v85
	v_fmac_f32_e32 v86, v111, v111
	v_and_b32_e32 v109, 0xffff0000, v85
	v_fmac_f32_e32 v86, v110, v110
	v_fmac_f32_e32 v86, v109, v109
	v_fmac_f32_e32 v86, v108, v108
	v_and_b32_e32 v104, 0xffff0000, v87
	v_lshlrev_b32_e32 v105, 16, v87
	v_fmac_f32_e32 v86, v107, v107
	v_pk_mul_f32 v[84:85], v[104:105], v[104:105]
	v_and_b32_e32 v102, 0xffff0000, v80
	v_add_f32_e32 v85, v85, v86
	v_lshlrev_b32_e32 v103, 16, v80
	v_add_f32_e32 v86, v84, v85
	v_pk_mul_f32 v[84:85], v[102:103], v[102:103]
	global_store_dwordx4 v[100:101], v[96:99], off offset:48
	v_add_f32_e32 v80, v85, v86
	v_and_b32_e32 v100, 0xffff0000, v81
	v_lshlrev_b32_e32 v101, 16, v81
	v_add_f32_e32 v84, v84, v80
	v_pk_mul_f32 v[80:81], v[100:101], v[100:101]
	v_and_b32_e32 v98, 0xffff0000, v82
	v_add_f32_e32 v81, v81, v84
	v_lshlrev_b32_e32 v99, 16, v82
	v_add_f32_e32 v84, v80, v81
	v_pk_mul_f32 v[80:81], v[98:99], v[98:99]
; template <int CTRL> __device__ __forceinline__ float dpp_f(float x) { return __int_as_float(__builtin_amdgcn_update_dpp(0, __float_as_int(x), CTRL, 0xF, 0xF, true)); }
; __device__ __forceinline__ void moba_prep_phase(unsigned char* lds, const bf16_t* H, const float* cosT, const float* sinT, const float* qgain, const float* kgain,
;                                                 bf16_t* Qn, bf16_t* Kimg, bf16_t* VT, float* kmean, int bid, int G, int tid) {
;     ...
;             for (int i = 0; i < 4; ++i) unpack8(raw[which][i], x + 8 * i);
;             float sq = 0.f;
; #pragma unroll
;             for (int i = 0; i < 32; ++i) sq += x[i] * x[i];
;             sq += dpp_f<DPP_XOR1>(sq);
;             const float rs = rsqrtf(sq * (1.0f / 64.0f) + 1e-6f);
; #pragma unroll
;             for (int i = 0; i < 32; ++i) { const float xn = x[i] * rs * gn[half * 32 + i]; const float other = dpp_f<DPP_XOR1>(xn); x[i] = half ? (xn * cs[i] + other * sn[i]) : (xn * cs[i] - other * sn[i]); }
	v_and_b32_e32 v96, 0xffff0000, v83
	v_add_f32_e32 v81, v81, v84
	v_lshlrev_b32_e32 v97, 16, v83
	v_add_f32_e32 v82, v80, v81
	v_pk_mul_f32 v[80:81], v[96:97], v[96:97]
	s_nop 0
	v_add_f32_e32 v81, v81, v82
	v_add_f32_e32 v80, v80, v81
	s_nop 1
	v_add_f32_dpp v80, v80, v80 quad_perm:[1,0,3,2] row_mask:0xf bank_mask:0xf bound_ctrl:1
	v_fmamk_f32 v80, v80, 0x3c800000, v137
	v_cmp_gt_f32_e64 s[0:1], s4, v80
	v_mul_f32_e32 v81, 0x4b800000, v80
	s_nop 0
	v_cndmask_b32_e64 v80, v80, v81, s[0:1]
	v_rsq_f32_e32 v80, v80
	s_nop 0
	v_mul_f32_e32 v81, 0x45800000, v80
	v_cndmask_b32_e64 v106, v80, v81, s[0:1]
	v_mov_b32_e32 v80, v236
	v_mov_b32_e32 v81, v237
	v_mov_b32_e32 v82, v238
	v_mov_b32_e32 v83, v239
	v_mov_b32_e32 v84, v232
	v_mov_b32_e32 v85, v233
	v_mov_b32_e32 v86, v234
	v_mov_b32_e32 v87, v235
	v_mov_b32_e32 v88, v228
	v_mov_b32_e32 v89, v229
	v_mov_b32_e32 v90, v230
	v_mov_b32_e32 v91, v231
	v_mov_b32_e32 v92, v220
	v_mov_b32_e32 v93, v221
	v_mov_b32_e32 v94, v222
	v_mov_b32_e32 v95, v223
	v_mul_f32_e32 v165, v106, v165
	v_mul_f32_e32 v166, v106, v166
	v_mul_f32_e32 v92, v92, v165
	s_nop 1
	v_mul_f32_dpp v165, v92, v20 quad_perm:[1,0,3,2] row_mask:0xf bank_mask:0xf bound_ctrl:1
	v_cndmask_b32_e64 v165, v165, -v165, vcc
	v_fmac_f32_e32 v165, v0, v92
	v_mul_f32_e32 v92, v106, v164
	v_mul_f32_e32 v92, v93, v92
	s_nop 1
	v_mul_f32_dpp v93, v92, v21 quad_perm:[1,0,3,2] row_mask:0xf bank_mask:0xf bound_ctrl:1
	v_cndmask_b32_e64 v164, v93, -v93, vcc
	v_fmac_f32_e32 v164, v1, v92
	v_mul_f32_e32 v92, v106, v163
	v_mul_f32_e32 v92, v94, v92
	s_nop 1
	v_mul_f32_dpp v93, v92, v22 quad_perm:[1,0,3,2] row_mask:0xf bank_mask:0xf bound_ctrl:1
	v_cndmask_b32_e64 v163, v93, -v93, vcc
	v_fmac_f32_e32 v163, v2, v92
	v_mul_f32_e32 v92, v106, v162
	v_mul_f32_e32 v92, v95, v92
	s_nop 1
	v_mul_f32_dpp v93, v92, v23 quad_perm:[1,0,3,2] row_mask:0xf bank_mask:0xf bound_ctrl:1
	v_cndmask_b32_e64 v162, v93, -v93, vcc
	v_fmac_f32_e32 v162, v3, v92
	v_mul_f32_e32 v92, v106, v153
	v_mul_f32_e32 v88, v88, v92
	s_nop 1
	v_mul_f32_dpp v92, v88, v24 quad_perm:[1,0,3,2] row_mask:0xf bank_mask:0xf bound_ctrl:1
	v_cndmask_b32_e64 v153, v92, -v92, vcc
	v_fmac_f32_e32 v153, v4, v88
	v_mul_f32_e32 v88, v106, v152
	v_mul_f32_e32 v88, v88, v89
	s_nop 1
	v_mul_f32_dpp v89, v88, v25 quad_perm:[1,0,3,2] row_mask:0xf bank_mask:0xf bound_ctrl:1
	v_cndmask_b32_e64 v152, v89, -v89, vcc
	v_fmac_f32_e32 v152, v5, v88
	v_mul_f32_e32 v88, v106, v151
	v_mul_f32_e32 v88, v88, v90
	s_nop 1
	v_mul_f32_dpp v89, v88, v26 quad_perm:[1,0,3,2] row_mask:0xf bank_mask:0xf bound_ctrl:1
	v_cndmask_b32_e64 v151, v89, -v89, vcc
	v_fmac_f32_e32 v151, v6, v88
	v_mul_f32_e32 v88, v106, v150
	v_mul_f32_e32 v88, v88, v91
	s_nop 1
	v_mul_f32_dpp v89, v88, v27 quad_perm:[1,0,3,2] row_mask:0xf bank_mask:0xf bound_ctrl:1
	v_cndmask_b32_e64 v150, v89, -v89, vcc
	v_fmac_f32_e32 v150, v7, v88
	v_mul_f32_e32 v88, v106, v149
	v_mul_f32_e32 v84, v88, v84
	s_nop 1
	v_mul_f32_dpp v88, v84, v28 quad_perm:[1,0,3,2] row_mask:0xf bank_mask:0xf bound_ctrl:1
	v_cndmask_b32_e64 v149, v88, -v88, vcc
	v_fmac_f32_e32 v149, v8, v84
	v_mul_f32_e32 v84, v106, v148
	v_mul_f32_e32 v84, v84, v85
	s_nop 1
	v_mul_f32_dpp v85, v84, v29 quad_perm:[1,0,3,2] row_mask:0xf bank_mask:0xf bound_ctrl:1
	v_cndmask_b32_e64 v148, v85, -v85, vcc
	v_fmac_f32_e32 v148, v9, v84
	v_mul_f32_e32 v84, v106, v135
	v_mul_f32_e32 v84, v84, v86
	s_nop 1
	v_mul_f32_dpp v85, v84, v30 quad_perm:[1,0,3,2] row_mask:0xf bank_mask:0xf bound_ctrl:1
	v_cndmask_b32_e64 v135, v85, -v85, vcc
	v_fmac_f32_e32 v135, v10, v84
	v_mul_f32_e32 v84, v106, v134
	v_mul_f32_e32 v84, v84, v87
	s_nop 1
	v_mul_f32_dpp v85, v84, v31 quad_perm:[1,0,3,2] row_mask:0xf bank_mask:0xf bound_ctrl:1
	v_cndmask_b32_e64 v134, v85, -v85, vcc
	v_fmac_f32_e32 v134, v11, v84
	v_mul_f32_e32 v84, v106, v133
	v_mul_f32_e32 v80, v84, v80
	s_nop 1
	v_mul_f32_dpp v84, v80, v32 quad_perm:[1,0,3,2] row_mask:0xf bank_mask:0xf bound_ctrl:1
	v_cndmask_b32_e64 v133, v84, -v84, vcc
	v_fmac_f32_e32 v133, v12, v80
	v_mul_f32_e32 v80, v106, v132
	v_mul_f32_e32 v80, v80, v81
	s_nop 1
	v_mul_f32_dpp v81, v80, v33 quad_perm:[1,0,3,2] row_mask:0xf bank_mask:0xf bound_ctrl:1
	v_cndmask_b32_e64 v132, v81, -v81, vcc
	v_fmac_f32_e32 v132, v13, v80
	v_mul_f32_e32 v80, v106, v131
	v_mul_f32_e32 v80, v80, v82
	s_nop 1
	v_mul_f32_dpp v81, v80, v34 quad_perm:[1,0,3,2] row_mask:0xf bank_mask:0xf bound_ctrl:1
	v_cndmask_b32_e64 v131, v81, -v81, vcc
	v_fmac_f32_e32 v131, v14, v80
	v_mul_f32_e32 v80, v106, v130
	v_mul_f32_e32 v80, v80, v83
	s_nop 1
	v_mul_f32_dpp v81, v80, v35 quad_perm:[1,0,3,2] row_mask:0xf bank_mask:0xf bound_ctrl:1
	v_cndmask_b32_e64 v130, v81, -v81, vcc
	v_fmac_f32_e32 v130, v15, v80
	v_mov_b32_e32 v80, v225
	v_mov_b32_e32 v81, v226
	v_mov_b32_e32 v82, v248
	v_mov_b32_e32 v83, v249
	v_mov_b32_e32 v84, v185
	v_mov_b32_e32 v85, v202
	v_mov_b32_e32 v86, v203
	v_mov_b32_e32 v87, v224
	v_mov_b32_e32 v88, v244
	v_mov_b32_e32 v89, v245
	v_mov_b32_e32 v90, v246
	v_mov_b32_e32 v91, v247
	v_mov_b32_e32 v92, v240
	v_mov_b32_e32 v93, v241
	v_mov_b32_e32 v94, v242
	v_mov_b32_e32 v95, v243
	s_waitcnt vmcnt(0)
; __device__ __forceinline__ u32x4 pack8(const float* f) { u32x4 w; w.x = cvt_pk_bf16(f[0], f[1]); w.y = cvt_pk_bf16(f[2], f[3]); w.z = cvt_pk_bf16(f[4], f[5]); w.w = cvt_pk_bf16(f[6], f[7]); return w; }
; template <int CTRL> __device__ __forceinline__ float dpp_f(float x) { return __int_as_float(__builtin_amdgcn_update_dpp(0, __float_as_int(x), CTRL, 0xF, 0xF, true)); }
; __device__ __forceinline__ void moba_prep_phase(unsigned char* lds, const bf16_t* H, const float* cosT, const float* sinT, const float* qgain, const float* kgain,
;                                                 bf16_t* Qn, bf16_t* Kimg, bf16_t* VT, float* kmean, int bid, int G, int tid) {
;     ...
;             for (int i = 0; i < 32; ++i) { const float xn = x[i] * rs * gn[half * 32 + i]; const float other = dpp_f<DPP_XOR1>(xn); x[i] = half ? (xn * cs[i] + other * sn[i]) : (xn * cs[i] - other * sn[i]); }
;             bf16_t* dst = which ? (Kimg + (size_t)(bh * 64 + n) * 16384 + tk * 64 + half * 32) : (Qn + ((size_t)bh * SEQ + t) * 64 + half * 32);
;             if (!which) {
; #pragma unroll
;                 for (int i = 0; i < 32; ++i) x[i] *= QSCALE;
;             }
; #pragma unroll
;             for (int i = 0; i < 4; ++i) *(u32x4*)(dst + 8 * i) = pack8(x + 8 * i);
;             if (which) {
; #pragma unroll
;                 for (int i = 0; i < 32; ++i) { float s = x[i]; s += dpp_f<DPP_XOR2>(s); s += dpp_f<DPP_ROR4>(s); s += dpp_f<DPP_ROR8>(s); if ((lane & 15) < 2) red[(wave * 4 + (lane >> 4)) * 64 + half * 32 + i] = s; }
	v_mul_f32_e32 v92, v166, v92
	s_nop 1
	v_mul_f32_dpp v166, v92, v36 quad_perm:[1,0,3,2] row_mask:0xf bank_mask:0xf bound_ctrl:1
	v_cndmask_b32_e64 v166, v166, -v166, vcc
	v_fmac_f32_e32 v166, v16, v92
	v_mul_f32_e32 v92, v106, v111
	v_mul_f32_e32 v92, v92, v93
	s_nop 1
	v_mul_f32_dpp v93, v92, v37 quad_perm:[1,0,3,2] row_mask:0xf bank_mask:0xf bound_ctrl:1
	v_cndmask_b32_e64 v111, v93, -v93, vcc
	v_fmac_f32_e32 v111, v17, v92
	v_mul_f32_e32 v92, v106, v110
	v_mul_f32_e32 v92, v92, v94
	s_nop 1
	v_mul_f32_dpp v93, v92, v38 quad_perm:[1,0,3,2] row_mask:0xf bank_mask:0xf bound_ctrl:1
	v_cndmask_b32_e64 v110, v93, -v93, vcc
	v_fmac_f32_e32 v110, v18, v92
	v_mul_f32_e32 v92, v106, v109
	v_mul_f32_e32 v92, v92, v95
	s_nop 1
	v_mul_f32_dpp v93, v92, v39 quad_perm:[1,0,3,2] row_mask:0xf bank_mask:0xf bound_ctrl:1
	v_cndmask_b32_e64 v95, v93, -v93, vcc
	v_fmac_f32_e32 v95, v19, v92
	v_mul_f32_e32 v92, v106, v108
	v_mul_f32_e32 v88, v92, v88
	s_nop 1
	v_mul_f32_dpp v92, v88, v40 quad_perm:[1,0,3,2] row_mask:0xf bank_mask:0xf bound_ctrl:1
	v_cndmask_b32_e64 v94, v92, -v92, vcc
	v_fmac_f32_e32 v94, v52, v88
	v_mul_f32_e32 v88, v106, v107
	v_mul_f32_e32 v88, v88, v89
	s_nop 1
	v_mul_f32_dpp v89, v88, v41 quad_perm:[1,0,3,2] row_mask:0xf bank_mask:0xf bound_ctrl:1
	v_cndmask_b32_e64 v93, v89, -v89, vcc
	v_fmac_f32_e32 v93, v53, v88
	v_mul_f32_e32 v88, v106, v105
	v_mul_f32_e32 v88, v88, v90
	s_nop 1
	v_mul_f32_dpp v89, v88, v42 quad_perm:[1,0,3,2] row_mask:0xf bank_mask:0xf bound_ctrl:1
	v_cndmask_b32_e64 v92, v89, -v89, vcc
	v_fmac_f32_e32 v92, v54, v88
	v_mul_f32_e32 v88, v106, v104
	v_mul_f32_e32 v88, v88, v91
	s_nop 1
	v_mul_f32_dpp v89, v88, v43 quad_perm:[1,0,3,2] row_mask:0xf bank_mask:0xf bound_ctrl:1
	v_cndmask_b32_e64 v91, v89, -v89, vcc
	v_fmac_f32_e32 v91, v55, v88
	v_mul_f32_e32 v88, v106, v103
	v_mul_f32_e32 v84, v88, v84
	s_nop 1
	v_mul_f32_dpp v88, v84, v44 quad_perm:[1,0,3,2] row_mask:0xf bank_mask:0xf bound_ctrl:1
	v_cndmask_b32_e64 v90, v88, -v88, vcc
	v_fmac_f32_e32 v90, v56, v84
	v_mul_f32_e32 v84, v106, v102
	v_mul_f32_e32 v84, v84, v85
	s_nop 1
	v_mul_f32_dpp v85, v84, v45 quad_perm:[1,0,3,2] row_mask:0xf bank_mask:0xf bound_ctrl:1
	v_cndmask_b32_e64 v89, v85, -v85, vcc
	v_fmac_f32_e32 v89, v57, v84
	v_mul_f32_e32 v84, v106, v101
	v_mul_f32_e32 v84, v84, v86
	s_nop 1
	v_mul_f32_dpp v85, v84, v46 quad_perm:[1,0,3,2] row_mask:0xf bank_mask:0xf bound_ctrl:1
	v_cndmask_b32_e64 v88, v85, -v85, vcc
	v_fmac_f32_e32 v88, v58, v84
	v_mul_f32_e32 v84, v106, v100
	v_mul_f32_e32 v84, v84, v87
	s_nop 1
	v_mul_f32_dpp v85, v84, v47 quad_perm:[1,0,3,2] row_mask:0xf bank_mask:0xf bound_ctrl:1
	v_cndmask_b32_e64 v86, v85, -v85, vcc
	v_fmac_f32_e32 v86, v59, v84
	v_mul_f32_e32 v84, v106, v99
	v_mul_f32_e32 v80, v84, v80
	s_nop 1
	v_mul_f32_dpp v84, v80, v48 quad_perm:[1,0,3,2] row_mask:0xf bank_mask:0xf bound_ctrl:1
	v_cndmask_b32_e64 v85, v84, -v84, vcc
	v_fmac_f32_e32 v85, v60, v80
	v_mul_f32_e32 v80, v106, v98
	v_mul_f32_e32 v80, v80, v81
	s_nop 1
	v_mul_f32_dpp v81, v80, v49 quad_perm:[1,0,3,2] row_mask:0xf bank_mask:0xf bound_ctrl:1
	v_cndmask_b32_e64 v84, v81, -v81, vcc
	v_fmac_f32_e32 v84, v61, v80
	v_mul_f32_e32 v80, v106, v97
	v_mul_f32_e32 v80, v80, v82
	s_nop 1
	v_mul_f32_dpp v81, v80, v50 quad_perm:[1,0,3,2] row_mask:0xf bank_mask:0xf bound_ctrl:1
	v_cndmask_b32_e64 v81, v81, -v81, vcc
	v_fmac_f32_e32 v81, v62, v80
	v_mul_f32_e32 v80, v106, v96
	v_mul_f32_e32 v82, v80, v83
	v_cvt_pk_bf16_f32 v96, v165, v164
	v_cvt_pk_bf16_f32 v97, v163, v162
	v_cvt_pk_bf16_f32 v98, v153, v152
	v_cvt_pk_bf16_f32 v99, v151, v150
	s_nop 1
	v_mul_f32_dpp v80, v82, v51 quad_perm:[1,0,3,2] row_mask:0xf bank_mask:0xf bound_ctrl:1
	v_cndmask_b32_e64 v80, v80, -v80, vcc
	v_fmac_f32_e32 v80, v63, v82
	v_lshl_add_u64 v[82:83], v[120:121], 0, s[40:41]
	global_store_dwordx4 v[82:83], v[96:99], off
	s_nop 1
	v_cvt_pk_bf16_f32 v96, v149, v148
	v_cvt_pk_bf16_f32 v97, v135, v134
	v_cvt_pk_bf16_f32 v98, v133, v132
	v_cvt_pk_bf16_f32 v99, v131, v130
	global_store_dwordx4 v[82:83], v[96:99], off offset:16
	s_nop 1
	v_cvt_pk_bf16_f32 v96, v166, v111
	v_cvt_pk_bf16_f32 v97, v110, v95
	v_cvt_pk_bf16_f32 v98, v94, v93
	v_cvt_pk_bf16_f32 v99, v92, v91
	global_store_dwordx4 v[82:83], v[96:99], off offset:32
	s_nop 1
	v_cvt_pk_bf16_f32 v96, v90, v89
	v_cvt_pk_bf16_f32 v97, v88, v86
	v_cvt_pk_bf16_f32 v98, v85, v84
	v_cvt_pk_bf16_f32 v99, v81, v80
	global_store_dwordx4 v[82:83], v[96:99], off offset:48
	v_add_f32_dpp v82, v165, v165 quad_perm:[2,3,0,1] row_mask:0xf bank_mask:0xf bound_ctrl:1
	s_nop 1
	v_add_f32_dpp v82, v82, v82 row_ror:4 row_mask:0xf bank_mask:0xf bound_ctrl:1
	s_nop 1
	v_mov_b32_dpp v83, v82 row_ror:8 row_mask:0xf bank_mask:0xf bound_ctrl:1
	s_and_saveexec_b64 s[0:1], s[36:37]
	v_add_f32_e32 v82, v82, v83
	ds_write_b32 v161, v82
	s_or_b64 exec, exec, s[0:1]
	v_add_f32_dpp v82, v164, v164 quad_perm:[2,3,0,1] row_mask:0xf bank_mask:0xf bound_ctrl:1
	s_nop 1
	v_add_f32_dpp v82, v82, v82 row_ror:4 row_mask:0xf bank_mask:0xf bound_ctrl:1
	s_nop 1
	v_mov_b32_dpp v83, v82 row_ror:8 row_mask:0xf bank_mask:0xf bound_ctrl:1
	s_and_saveexec_b64 s[0:1], s[36:37]
	v_add_f32_e32 v82, v82, v83
	ds_write_b32 v161, v82 offset:4
	s_or_b64 exec, exec, s[0:1]
	v_add_f32_dpp v82, v163, v163 quad_perm:[2,3,0,1] row_mask:0xf bank_mask:0xf bound_ctrl:1
	s_nop 1
	v_add_f32_dpp v82, v82, v82 row_ror:4 row_mask:0xf bank_mask:0xf bound_ctrl:1
	s_nop 1
	v_mov_b32_dpp v83, v82 row_ror:8 row_mask:0xf bank_mask:0xf bound_ctrl:1
	s_and_saveexec_b64 s[0:1], s[36:37]
	v_add_f32_e32 v82, v82, v83
	ds_write_b32 v161, v82 offset:8
	s_or_b64 exec, exec, s[0:1]
; template <int CTRL> __device__ __forceinline__ float dpp_f(float x) { return __int_as_float(__builtin_amdgcn_update_dpp(0, __float_as_int(x), CTRL, 0xF, 0xF, true)); }
; __device__ __forceinline__ void moba_prep_phase(unsigned char* lds, const bf16_t* H, const float* cosT, const float* sinT, const float* qgain, const float* kgain,
;                                                 bf16_t* Qn, bf16_t* Kimg, bf16_t* VT, float* kmean, int bid, int G, int tid) {
;     ...
; #pragma unroll
;                 for (int i = 0; i < 32; ++i) { float s = x[i]; s += dpp_f<DPP_XOR2>(s); s += dpp_f<DPP_ROR4>(s); s += dpp_f<DPP_ROR8>(s); if ((lane & 15) < 2) red[(wave * 4 + (lane >> 4)) * 64 + half * 32 + i] = s; }
;             }
	v_add_f32_dpp v82, v162, v162 quad_perm:[2,3,0,1] row_mask:0xf bank_mask:0xf bound_ctrl:1
	s_nop 1
	v_add_f32_dpp v82, v82, v82 row_ror:4 row_mask:0xf bank_mask:0xf bound_ctrl:1
	s_nop 1
	v_mov_b32_dpp v83, v82 row_ror:8 row_mask:0xf bank_mask:0xf bound_ctrl:1
	s_and_saveexec_b64 s[0:1], s[36:37]
	v_add_f32_e32 v82, v82, v83
	ds_write_b32 v161, v82 offset:12
	s_or_b64 exec, exec, s[0:1]
	v_add_f32_dpp v82, v153, v153 quad_perm:[2,3,0,1] row_mask:0xf bank_mask:0xf bound_ctrl:1
	s_nop 1
	v_add_f32_dpp v82, v82, v82 row_ror:4 row_mask:0xf bank_mask:0xf bound_ctrl:1
	s_nop 1
	v_mov_b32_dpp v83, v82 row_ror:8 row_mask:0xf bank_mask:0xf bound_ctrl:1
	s_and_saveexec_b64 s[0:1], s[36:37]
	v_add_f32_e32 v82, v82, v83
	ds_write_b32 v161, v82 offset:16
	s_or_b64 exec, exec, s[0:1]
	v_add_f32_dpp v82, v152, v152 quad_perm:[2,3,0,1] row_mask:0xf bank_mask:0xf bound_ctrl:1
	s_nop 1
	v_add_f32_dpp v82, v82, v82 row_ror:4 row_mask:0xf bank_mask:0xf bound_ctrl:1
	s_nop 1
	v_mov_b32_dpp v83, v82 row_ror:8 row_mask:0xf bank_mask:0xf bound_ctrl:1
	s_and_saveexec_b64 s[0:1], s[36:37]
	v_add_f32_e32 v82, v82, v83
	ds_write_b32 v161, v82 offset:20
	s_or_b64 exec, exec, s[0:1]
	v_add_f32_dpp v82, v151, v151 quad_perm:[2,3,0,1] row_mask:0xf bank_mask:0xf bound_ctrl:1
	s_nop 1
	v_add_f32_dpp v82, v82, v82 row_ror:4 row_mask:0xf bank_mask:0xf bound_ctrl:1
	s_nop 1
	v_mov_b32_dpp v83, v82 row_ror:8 row_mask:0xf bank_mask:0xf bound_ctrl:1
	s_and_saveexec_b64 s[0:1], s[36:37]
	v_add_f32_e32 v82, v82, v83
	ds_write_b32 v161, v82 offset:24
	s_or_b64 exec, exec, s[0:1]
	v_add_f32_dpp v82, v150, v150 quad_perm:[2,3,0,1] row_mask:0xf bank_mask:0xf bound_ctrl:1
	s_nop 1
	v_add_f32_dpp v82, v82, v82 row_ror:4 row_mask:0xf bank_mask:0xf bound_ctrl:1
	s_nop 1
	v_mov_b32_dpp v83, v82 row_ror:8 row_mask:0xf bank_mask:0xf bound_ctrl:1
	s_and_saveexec_b64 s[0:1], s[36:37]
	v_add_f32_e32 v82, v82, v83
	ds_write_b32 v161, v82 offset:28
	s_or_b64 exec, exec, s[0:1]
	v_add_f32_dpp v82, v149, v149 quad_perm:[2,3,0,1] row_mask:0xf bank_mask:0xf bound_ctrl:1
	s_nop 1
	v_add_f32_dpp v82, v82, v82 row_ror:4 row_mask:0xf bank_mask:0xf bound_ctrl:1
	s_nop 1
	v_mov_b32_dpp v83, v82 row_ror:8 row_mask:0xf bank_mask:0xf bound_ctrl:1
	s_and_saveexec_b64 s[0:1], s[36:37]
	v_add_f32_e32 v82, v82, v83
	ds_write_b32 v161, v82 offset:32
	s_or_b64 exec, exec, s[0:1]
	v_add_f32_dpp v82, v148, v148 quad_perm:[2,3,0,1] row_mask:0xf bank_mask:0xf bound_ctrl:1
	s_nop 1
	v_add_f32_dpp v82, v82, v82 row_ror:4 row_mask:0xf bank_mask:0xf bound_ctrl:1
	s_nop 1
	v_mov_b32_dpp v83, v82 row_ror:8 row_mask:0xf bank_mask:0xf bound_ctrl:1
	s_and_saveexec_b64 s[0:1], s[36:37]
	v_add_f32_e32 v82, v82, v83
	ds_write_b32 v161, v82 offset:36
	s_or_b64 exec, exec, s[0:1]
	v_add_f32_dpp v82, v135, v135 quad_perm:[2,3,0,1] row_mask:0xf bank_mask:0xf bound_ctrl:1
	s_nop 1
	v_add_f32_dpp v82, v82, v82 row_ror:4 row_mask:0xf bank_mask:0xf bound_ctrl:1
	s_nop 1
	v_mov_b32_dpp v83, v82 row_ror:8 row_mask:0xf bank_mask:0xf bound_ctrl:1
	s_and_saveexec_b64 s[0:1], s[36:37]
	v_add_f32_e32 v82, v82, v83
	ds_write_b32 v161, v82 offset:40
	s_or_b64 exec, exec, s[0:1]
	v_add_f32_dpp v82, v134, v134 quad_perm:[2,3,0,1] row_mask:0xf bank_mask:0xf bound_ctrl:1
	s_nop 1
	v_add_f32_dpp v82, v82, v82 row_ror:4 row_mask:0xf bank_mask:0xf bound_ctrl:1
	s_nop 1
	v_mov_b32_dpp v83, v82 row_ror:8 row_mask:0xf bank_mask:0xf bound_ctrl:1
	s_and_saveexec_b64 s[0:1], s[36:37]
	v_add_f32_e32 v82, v82, v83
	ds_write_b32 v161, v82 offset:44
	s_or_b64 exec, exec, s[0:1]
	v_add_f32_dpp v82, v133, v133 quad_perm:[2,3,0,1] row_mask:0xf bank_mask:0xf bound_ctrl:1
	s_nop 1
	v_add_f32_dpp v82, v82, v82 row_ror:4 row_mask:0xf bank_mask:0xf bound_ctrl:1
	s_nop 1
	v_mov_b32_dpp v83, v82 row_ror:8 row_mask:0xf bank_mask:0xf bound_ctrl:1
	s_and_saveexec_b64 s[0:1], s[36:37]
	v_add_f32_e32 v82, v82, v83
	ds_write_b32 v161, v82 offset:48
	s_or_b64 exec, exec, s[0:1]
	v_add_f32_dpp v82, v132, v132 quad_perm:[2,3,0,1] row_mask:0xf bank_mask:0xf bound_ctrl:1
	s_nop 1
	v_add_f32_dpp v82, v82, v82 row_ror:4 row_mask:0xf bank_mask:0xf bound_ctrl:1
	s_nop 1
	v_mov_b32_dpp v83, v82 row_ror:8 row_mask:0xf bank_mask:0xf bound_ctrl:1
	s_and_saveexec_b64 s[0:1], s[36:37]
	v_add_f32_e32 v82, v82, v83
	ds_write_b32 v161, v82 offset:52
	s_or_b64 exec, exec, s[0:1]
	v_add_f32_dpp v82, v131, v131 quad_perm:[2,3,0,1] row_mask:0xf bank_mask:0xf bound_ctrl:1
	s_nop 1
	v_add_f32_dpp v82, v82, v82 row_ror:4 row_mask:0xf bank_mask:0xf bound_ctrl:1
	s_nop 1
	v_mov_b32_dpp v83, v82 row_ror:8 row_mask:0xf bank_mask:0xf bound_ctrl:1
	s_and_saveexec_b64 s[0:1], s[36:37]
	v_add_f32_e32 v82, v82, v83
	ds_write_b32 v161, v82 offset:56
	s_or_b64 exec, exec, s[0:1]
	v_add_f32_dpp v82, v130, v130 quad_perm:[2,3,0,1] row_mask:0xf bank_mask:0xf bound_ctrl:1
	s_nop 1
	v_add_f32_dpp v82, v82, v82 row_ror:4 row_mask:0xf bank_mask:0xf bound_ctrl:1
	s_nop 1
	v_mov_b32_dpp v83, v82 row_ror:8 row_mask:0xf bank_mask:0xf bound_ctrl:1
	s_and_saveexec_b64 s[0:1], s[36:37]
	v_add_f32_e32 v82, v82, v83
	ds_write_b32 v161, v82 offset:60
	s_or_b64 exec, exec, s[0:1]
	v_add_f32_dpp v82, v166, v166 quad_perm:[2,3,0,1] row_mask:0xf bank_mask:0xf bound_ctrl:1
	s_nop 1
	v_add_f32_dpp v82, v82, v82 row_ror:4 row_mask:0xf bank_mask:0xf bound_ctrl:1
	s_nop 1
	v_mov_b32_dpp v83, v82 row_ror:8 row_mask:0xf bank_mask:0xf bound_ctrl:1
	s_and_saveexec_b64 s[0:1], s[36:37]
	v_add_f32_e32 v82, v82, v83
	ds_write_b32 v161, v82 offset:64
	s_or_b64 exec, exec, s[0:1]
	v_add_f32_dpp v82, v111, v111 quad_perm:[2,3,0,1] row_mask:0xf bank_mask:0xf bound_ctrl:1
	s_nop 1
	v_add_f32_dpp v82, v82, v82 row_ror:4 row_mask:0xf bank_mask:0xf bound_ctrl:1
; template <int CTRL> __device__ __forceinline__ float dpp_f(float x) { return __int_as_float(__builtin_amdgcn_update_dpp(0, __float_as_int(x), CTRL, 0xF, 0xF, true)); }
; __device__ __forceinline__ int vperm(int k) { return (k & ~31) + (((k & 15) >> 2) << 3) + (((k >> 4) & 1) << 2) + (k & 3); }
; __device__ __forceinline__ void moba_prep_phase(unsigned char* lds, const bf16_t* H, const float* cosT, const float* sinT, const float* qgain, const float* kgain,
;                                                 bf16_t* Qn, bf16_t* Kimg, bf16_t* VT, float* kmean, int bid, int G, int tid) {
;     ...
;                 for (int i = 0; i < 32; ++i) { float s = x[i]; s += dpp_f<DPP_XOR2>(s); s += dpp_f<DPP_ROR4>(s); s += dpp_f<DPP_ROR8>(s); if ((lane & 15) < 2) red[(wave * 4 + (lane >> 4)) * 64 + half * 32 + i] = s; }
;             }
;         }
;         {
; #pragma unroll
;             for (int i = 0; i < 4; ++i) { const u32x4 w = raw[2][i]; const unsigned ww[4] = {w.x, w.y, w.z, w.w};
; #pragma unroll
;                 for (int e = 0; e < 4; ++e) { *(unsigned short*)(vts + (half * 32 + 8 * i + 2 * e) * 528 + vperm(tk) * 2) = (unsigned short)(ww[e] & 0xffffu); *(unsigned short*)(vts + (half * 32 + 8 * i + 2 * e + 1) * 528 + vperm(tk) * 2) = (unsigned short)(ww[e] >> 16); } }
;         }
;         __syncthreads();
	s_nop 1
	v_mov_b32_dpp v83, v82 row_ror:8 row_mask:0xf bank_mask:0xf bound_ctrl:1
	s_and_saveexec_b64 s[0:1], s[36:37]
	v_add_f32_e32 v82, v82, v83
	ds_write_b32 v161, v82 offset:68
	s_or_b64 exec, exec, s[0:1]
	v_add_f32_dpp v82, v110, v110 quad_perm:[2,3,0,1] row_mask:0xf bank_mask:0xf bound_ctrl:1
	s_nop 1
	v_add_f32_dpp v82, v82, v82 row_ror:4 row_mask:0xf bank_mask:0xf bound_ctrl:1
	s_nop 1
	v_mov_b32_dpp v83, v82 row_ror:8 row_mask:0xf bank_mask:0xf bound_ctrl:1
	s_and_saveexec_b64 s[0:1], s[36:37]
	v_add_f32_e32 v82, v82, v83
	ds_write_b32 v161, v82 offset:72
	s_or_b64 exec, exec, s[0:1]
	v_add_f32_dpp v82, v95, v95 quad_perm:[2,3,0,1] row_mask:0xf bank_mask:0xf bound_ctrl:1
	s_nop 1
	v_add_f32_dpp v82, v82, v82 row_ror:4 row_mask:0xf bank_mask:0xf bound_ctrl:1
	s_nop 1
	v_mov_b32_dpp v83, v82 row_ror:8 row_mask:0xf bank_mask:0xf bound_ctrl:1
	s_and_saveexec_b64 s[0:1], s[36:37]
	v_add_f32_e32 v82, v82, v83
	ds_write_b32 v161, v82 offset:76
	s_or_b64 exec, exec, s[0:1]
	v_add_f32_dpp v82, v94, v94 quad_perm:[2,3,0,1] row_mask:0xf bank_mask:0xf bound_ctrl:1
	s_nop 1
	v_add_f32_dpp v82, v82, v82 row_ror:4 row_mask:0xf bank_mask:0xf bound_ctrl:1
	s_nop 1
	v_mov_b32_dpp v83, v82 row_ror:8 row_mask:0xf bank_mask:0xf bound_ctrl:1
	s_and_saveexec_b64 s[0:1], s[36:37]
	v_add_f32_e32 v82, v82, v83
	ds_write_b32 v161, v82 offset:80
	s_or_b64 exec, exec, s[0:1]
	v_add_f32_dpp v82, v93, v93 quad_perm:[2,3,0,1] row_mask:0xf bank_mask:0xf bound_ctrl:1
	s_nop 1
	v_add_f32_dpp v82, v82, v82 row_ror:4 row_mask:0xf bank_mask:0xf bound_ctrl:1
	s_nop 1
	v_mov_b32_dpp v83, v82 row_ror:8 row_mask:0xf bank_mask:0xf bound_ctrl:1
	s_and_saveexec_b64 s[0:1], s[36:37]
	v_add_f32_e32 v82, v82, v83
	ds_write_b32 v161, v82 offset:84
	s_or_b64 exec, exec, s[0:1]
	v_add_f32_dpp v82, v92, v92 quad_perm:[2,3,0,1] row_mask:0xf bank_mask:0xf bound_ctrl:1
	s_nop 1
	v_add_f32_dpp v82, v82, v82 row_ror:4 row_mask:0xf bank_mask:0xf bound_ctrl:1
	s_nop 1
	v_mov_b32_dpp v83, v82 row_ror:8 row_mask:0xf bank_mask:0xf bound_ctrl:1
	s_and_saveexec_b64 s[0:1], s[36:37]
	v_add_f32_e32 v82, v82, v83
	ds_write_b32 v161, v82 offset:88
	s_or_b64 exec, exec, s[0:1]
	v_add_f32_dpp v82, v91, v91 quad_perm:[2,3,0,1] row_mask:0xf bank_mask:0xf bound_ctrl:1
	s_nop 1
	v_add_f32_dpp v82, v82, v82 row_ror:4 row_mask:0xf bank_mask:0xf bound_ctrl:1
	s_nop 1
	v_mov_b32_dpp v83, v82 row_ror:8 row_mask:0xf bank_mask:0xf bound_ctrl:1
	s_and_saveexec_b64 s[0:1], s[36:37]
	v_add_f32_e32 v82, v82, v83
	ds_write_b32 v161, v82 offset:92
	s_or_b64 exec, exec, s[0:1]
	v_add_f32_dpp v82, v90, v90 quad_perm:[2,3,0,1] row_mask:0xf bank_mask:0xf bound_ctrl:1
	s_nop 1
	v_add_f32_dpp v82, v82, v82 row_ror:4 row_mask:0xf bank_mask:0xf bound_ctrl:1
	s_nop 1
	v_mov_b32_dpp v83, v82 row_ror:8 row_mask:0xf bank_mask:0xf bound_ctrl:1
	s_and_saveexec_b64 s[0:1], s[36:37]
	v_add_f32_e32 v82, v82, v83
	ds_write_b32 v161, v82 offset:96
	s_or_b64 exec, exec, s[0:1]
	v_add_f32_dpp v82, v89, v89 quad_perm:[2,3,0,1] row_mask:0xf bank_mask:0xf bound_ctrl:1
	s_nop 1
	v_add_f32_dpp v82, v82, v82 row_ror:4 row_mask:0xf bank_mask:0xf bound_ctrl:1
	s_nop 1
	v_mov_b32_dpp v83, v82 row_ror:8 row_mask:0xf bank_mask:0xf bound_ctrl:1
	s_and_saveexec_b64 s[0:1], s[36:37]
	v_add_f32_e32 v82, v82, v83
	ds_write_b32 v161, v82 offset:100
	s_or_b64 exec, exec, s[0:1]
	v_add_f32_dpp v82, v88, v88 quad_perm:[2,3,0,1] row_mask:0xf bank_mask:0xf bound_ctrl:1
	s_nop 1
	v_add_f32_dpp v82, v82, v82 row_ror:4 row_mask:0xf bank_mask:0xf bound_ctrl:1
	s_nop 1
	v_mov_b32_dpp v83, v82 row_ror:8 row_mask:0xf bank_mask:0xf bound_ctrl:1
	s_and_saveexec_b64 s[0:1], s[36:37]
	v_add_f32_e32 v82, v82, v83
	ds_write_b32 v161, v82 offset:104
	s_or_b64 exec, exec, s[0:1]
	v_add_f32_dpp v82, v86, v86 quad_perm:[2,3,0,1] row_mask:0xf bank_mask:0xf bound_ctrl:1
	s_nop 1
	v_add_f32_dpp v82, v82, v82 row_ror:4 row_mask:0xf bank_mask:0xf bound_ctrl:1
	s_nop 1
	v_mov_b32_dpp v83, v82 row_ror:8 row_mask:0xf bank_mask:0xf bound_ctrl:1
	s_and_saveexec_b64 s[0:1], s[36:37]
	v_add_f32_e32 v82, v82, v83
	ds_write_b32 v161, v82 offset:108
	s_or_b64 exec, exec, s[0:1]
	v_add_f32_dpp v82, v85, v85 quad_perm:[2,3,0,1] row_mask:0xf bank_mask:0xf bound_ctrl:1
	s_nop 1
	v_add_f32_dpp v82, v82, v82 row_ror:4 row_mask:0xf bank_mask:0xf bound_ctrl:1
	s_nop 1
	v_mov_b32_dpp v83, v82 row_ror:8 row_mask:0xf bank_mask:0xf bound_ctrl:1
	s_and_saveexec_b64 s[0:1], s[36:37]
	v_add_f32_e32 v82, v82, v83
	ds_write_b32 v161, v82 offset:112
	s_or_b64 exec, exec, s[0:1]
	v_add_f32_dpp v82, v84, v84 quad_perm:[2,3,0,1] row_mask:0xf bank_mask:0xf bound_ctrl:1
	s_nop 1
	v_add_f32_dpp v82, v82, v82 row_ror:4 row_mask:0xf bank_mask:0xf bound_ctrl:1
	s_nop 1
	v_mov_b32_dpp v83, v82 row_ror:8 row_mask:0xf bank_mask:0xf bound_ctrl:1
	s_and_saveexec_b64 s[0:1], s[36:37]
	v_add_f32_e32 v82, v82, v83
	ds_write_b32 v161, v82 offset:116
	s_or_b64 exec, exec, s[0:1]
	v_add_f32_dpp v81, v81, v81 quad_perm:[2,3,0,1] row_mask:0xf bank_mask:0xf bound_ctrl:1
	s_nop 1
	v_add_f32_dpp v81, v81, v81 row_ror:4 row_mask:0xf bank_mask:0xf bound_ctrl:1
	s_nop 1
	v_mov_b32_dpp v82, v81 row_ror:8 row_mask:0xf bank_mask:0xf bound_ctrl:1
	s_and_saveexec_b64 s[0:1], s[36:37]
	v_add_f32_e32 v81, v81, v82
	ds_write_b32 v161, v81 offset:120
	s_or_b64 exec, exec, s[0:1]
	v_add_f32_dpp v80, v80, v80 quad_perm:[2,3,0,1] row_mask:0xf bank_mask:0xf bound_ctrl:1
	s_nop 1
	v_add_f32_dpp v80, v80, v80 row_ror:4 row_mask:0xf bank_mask:0xf bound_ctrl:1
	s_nop 1
	v_mov_b32_dpp v81, v80 row_ror:8 row_mask:0xf bank_mask:0xf bound_ctrl:1
	s_and_saveexec_b64 s[0:1], s[36:37]
	v_add_f32_e32 v80, v80, v81
	ds_write_b32 v161, v80 offset:124
	s_or_b64 exec, exec, s[0:1]
	ds_write_b16 v156, v76 offset:8192
	ds_write_b16_d16_hi v156, v76 offset:8720
	ds_write_b16 v156, v77 offset:9248
	ds_write_b16_d16_hi v156, v77 offset:9776
	ds_write_b16 v156, v78 offset:10304
	ds_write_b16_d16_hi v156, v78 offset:10832
	ds_write_b16 v156, v79 offset:11360
	ds_write_b16_d16_hi v156, v79 offset:11888
	ds_write_b16 v156, v72 offset:12416
	ds_write_b16_d16_hi v156, v72 offset:12944
	ds_write_b16 v156, v73 offset:13472
	ds_write_b16_d16_hi v156, v73 offset:14000
	ds_write_b16 v156, v74 offset:14528
	ds_write_b16_d16_hi v156, v74 offset:15056
	ds_write_b16 v156, v75 offset:15584
	ds_write_b16_d16_hi v156, v75 offset:16112
	ds_write_b16 v156, v68 offset:16640
	ds_write_b16_d16_hi v156, v68 offset:17168
	ds_write_b16 v156, v69 offset:17696
	ds_write_b16_d16_hi v156, v69 offset:18224
	ds_write_b16 v156, v70 offset:18752
	ds_write_b16_d16_hi v156, v70 offset:19280
	ds_write_b16 v156, v71 offset:19808
	ds_write_b16_d16_hi v156, v71 offset:20336
	ds_write_b16 v156, v64 offset:20864
	ds_write_b16_d16_hi v156, v64 offset:21392
	ds_write_b16 v156, v65 offset:21920
	ds_write_b16_d16_hi v156, v65 offset:22448
	ds_write_b16 v156, v66 offset:22976
	ds_write_b16_d16_hi v156, v66 offset:23504
	ds_write_b16 v156, v67 offset:24032
	ds_write_b16_d16_hi v156, v67 offset:24560
	s_waitcnt lgkmcnt(0)
	s_barrier
; __device__ __forceinline__ void moba_prep_phase(unsigned char* lds, const bf16_t* H, const float* cosT, const float* sinT, const float* qgain, const float* kgain,
;                                                 bf16_t* Qn, bf16_t* Kimg, bf16_t* VT, float* kmean, int bid, int G, int tid) {
;     ...
;         if (tid < 64) { float s = 0.f;
; #pragma unroll
;             for (int w = 0; w < 32; ++w) s += red[w * 64 + tid];
;             kmean[(size_t)(bh * 64 + n) * 64 + tid] = s * (1.0f / 256.0f); }
	s_and_saveexec_b64 s[0:1], s[38:39]
	s_cbranch_execz .LBB0_502
	ds_read2st64_b32 v[64:65], v155 offset1:1
	s_lshl_b64 s[26:27], s[46:47], 8
	s_waitcnt lgkmcnt(0)
	v_add_f32_e32 v64, 0, v64
	v_add_f32_e32 v66, v64, v65
	ds_read2st64_b32 v[64:65], v155 offset0:2 offset1:3
	s_waitcnt lgkmcnt(0)
	v_add_f32_e32 v64, v66, v64
	v_add_f32_e32 v66, v64, v65
	ds_read2st64_b32 v[64:65], v155 offset0:4 offset1:5
	s_waitcnt lgkmcnt(0)
	v_add_f32_e32 v64, v66, v64
	v_add_f32_e32 v66, v64, v65
	ds_read2st64_b32 v[64:65], v155 offset0:6 offset1:7
	s_waitcnt lgkmcnt(0)
	v_add_f32_e32 v64, v66, v64
	v_add_f32_e32 v66, v64, v65
	ds_read2st64_b32 v[64:65], v155 offset0:8 offset1:9
	s_waitcnt lgkmcnt(0)
	v_add_f32_e32 v64, v66, v64
	v_add_f32_e32 v66, v64, v65
	ds_read2st64_b32 v[64:65], v155 offset0:10 offset1:11
	s_waitcnt lgkmcnt(0)
	v_add_f32_e32 v64, v66, v64
	v_add_f32_e32 v66, v64, v65
	ds_read2st64_b32 v[64:65], v155 offset0:12 offset1:13
	s_waitcnt lgkmcnt(0)
	v_add_f32_e32 v64, v66, v64
	v_add_f32_e32 v66, v64, v65
	ds_read2st64_b32 v[64:65], v155 offset0:14 offset1:15
	s_waitcnt lgkmcnt(0)
	v_add_f32_e32 v64, v66, v64
	v_add_f32_e32 v66, v64, v65
	ds_read2st64_b32 v[64:65], v155 offset0:16 offset1:17
	s_waitcnt lgkmcnt(0)
	v_add_f32_e32 v64, v66, v64
	v_add_f32_e32 v66, v64, v65
	ds_read2st64_b32 v[64:65], v155 offset0:18 offset1:19
	s_waitcnt lgkmcnt(0)
	v_add_f32_e32 v64, v66, v64
	v_add_f32_e32 v66, v64, v65
	ds_read2st64_b32 v[64:65], v155 offset0:20 offset1:21
	s_waitcnt lgkmcnt(0)
	v_add_f32_e32 v64, v66, v64
	v_add_f32_e32 v66, v64, v65
	ds_read2st64_b32 v[64:65], v155 offset0:22 offset1:23
	s_waitcnt lgkmcnt(0)
	v_add_f32_e32 v64, v66, v64
	v_add_f32_e32 v66, v64, v65
	ds_read2st64_b32 v[64:65], v155 offset0:24 offset1:25
	s_waitcnt lgkmcnt(0)
	v_add_f32_e32 v64, v66, v64
	v_add_f32_e32 v66, v64, v65
	ds_read2st64_b32 v[64:65], v155 offset0:26 offset1:27
	s_waitcnt lgkmcnt(0)
	v_add_f32_e32 v64, v66, v64
	v_add_f32_e32 v66, v64, v65
	ds_read2st64_b32 v[64:65], v155 offset0:28 offset1:29
	s_waitcnt lgkmcnt(0)
	v_add_f32_e32 v64, v66, v64
	v_add_f32_e32 v66, v64, v65
	ds_read2st64_b32 v[64:65], v155 offset0:30 offset1:31
	s_waitcnt lgkmcnt(0)
	v_add_f32_e32 v64, v66, v64
	v_add_f32_e32 v64, v64, v65
	v_mul_f32_e32 v66, 0x3b800000, v64
	v_lshl_add_u64 v[64:65], v[112:113], 0, s[26:27]
	global_store_dword v[64:65], v66, off
	s_branch .LBB0_502
